# gMLP unit core rewritten: A fragments via ds_read_b64_tr_b16 (2 per MFMA) replacing 8 ds_read_u16 + perms, reads batched ahead
# baseline (speedup 1.0000x reference)
.Lgm_keep:
	v_lshrrev_b32_e32 v129, 4, v233
	v_bfe_u32 v128, v233, 2, 2
	v_mul_u32_u24_e32 v129, 0x480, v129
	v_mul_u32_u24_e32 v128, 0x90, v128
	v_add_u32_e32 v129, v129, v128
	v_and_b32_e32 v128, 3, v233
	v_lshl_add_u32 v129, v128, 3, v129
.LBB0_968:
	s_lshl_b32 s6, s15, 7
	s_and_b32 s6, s6, 0x180
	s_or_b32 s80, s6, s9
	s_and_b32 s16, s14, 0xffffff80
	v_lshl_add_u64 v[2:3], s[80:81], 0, v[18:19]
	v_lshlrev_b64 v[10:11], 9, v[2:3]
	v_add_u32_e32 v2, s16, v36
	v_ashrrev_i32_e32 v3, 31, v2
	v_lshlrev_b64 v[2:3], 9, v[2:3]
	v_lshl_add_u64 v[2:3], s[0:1], 0, v[2:3]
	s_mov_b32 s7, s81
	v_lshl_add_u64 v[2:3], v[2:3], 0, s[6:7]
	v_lshl_add_u64 v[6:7], v[2:3], 0, v[0:1]
	v_lshl_add_u64 v[24:25], v[20:21], 0, v[10:11]
	global_load_dwordx4 v[2:5], v[6:7], off offset:16
	s_nop 0
	global_load_dwordx4 v[6:9], v[6:7], off
	s_nop 0
	global_load_dwordx4 v[10:13], v[24:25], off offset:16
	global_load_dwordx4 v[14:17], v[24:25], off
	global_load_dwordx4 v[30:33], v[24:25], off offset:144
	global_load_dwordx4 v[40:43], v[24:25], off offset:128
	global_load_dwordx4 v[44:47], v[24:25], off offset:272
	global_load_dwordx4 v[48:51], v[24:25], off offset:256
	global_load_dwordx4 v[52:55], v[24:25], off offset:400
	global_load_dwordx4 v[56:59], v[24:25], off offset:384
	v_add_u32_e32 v24, s80, v18
	v_ashrrev_i32_e32 v25, 31, v24
	v_add_u32_e32 v34, s16, v18
	v_lshl_add_u64 v[24:25], v[24:25], 2, v[132:133]
	v_ashrrev_i32_e32 v35, 31, v34
	global_load_dword v39, v[24:25], off
	v_lshlrev_b64 v[24:25], 9, v[34:35]
	v_lshl_add_u64 v[24:25], s[4:5], 0, v[24:25]
	v_lshl_add_u64 v[24:25], v[24:25], 0, s[6:7]
	v_mov_b32_e32 v23, v1
	v_lshl_add_u64 v[24:25], v[24:25], 0, v[22:23]
	global_load_dwordx2 v[60:61], v[24:25], off
	global_load_dwordx2 v[28:29], v[24:25], off offset:32
	global_load_dwordx2 v[26:27], v[24:25], off offset:64
	s_nop 0
	global_load_dwordx2 v[24:25], v[24:25], off offset:96
	s_add_i32 s15, s15, s100
	s_add_i32 s14, s14, s101
	s_cmp_ge_i32 s15, s8
	s_waitcnt vmcnt(13)
	ds_write_b128 v37, v[6:9]
	ds_write_b128 v37, v[2:5] offset:16
	s_waitcnt lgkmcnt(0)
	s_barrier
	ds_read_b64_tr_b16 v[64:65], v129
	ds_read_b64_tr_b16 v[66:67], v129 offset:576
	ds_read_b64_tr_b16 v[68:69], v129 offset:4608
	ds_read_b64_tr_b16 v[70:71], v129 offset:5184
	ds_read_b64_tr_b16 v[72:73], v129 offset:9216
	ds_read_b64_tr_b16 v[74:75], v129 offset:9792
	ds_read_b64_tr_b16 v[76:77], v129 offset:13824
	ds_read_b64_tr_b16 v[78:79], v129 offset:14400
	ds_read_b64_tr_b16 v[80:81], v129 offset:32
	ds_read_b64_tr_b16 v[82:83], v129 offset:608
	ds_read_b64_tr_b16 v[84:85], v129 offset:4640
	ds_read_b64_tr_b16 v[86:87], v129 offset:5216
	s_waitcnt vmcnt(11)
	v_cvt_pk_bf16_f32 v14, v14, v15
	v_cvt_pk_bf16_f32 v15, v16, v17
	v_cvt_pk_bf16_f32 v16, v10, v11
	v_cvt_pk_bf16_f32 v17, v12, v13
	s_waitcnt vmcnt(9)
	v_cvt_pk_bf16_f32 v10, v40, v41
	v_cvt_pk_bf16_f32 v11, v42, v43
	v_cvt_pk_bf16_f32 v12, v30, v31
	v_cvt_pk_bf16_f32 v13, v32, v33
	s_waitcnt vmcnt(7)
	v_cvt_pk_bf16_f32 v6, v48, v49
	v_cvt_pk_bf16_f32 v7, v50, v51
	v_cvt_pk_bf16_f32 v8, v44, v45
	v_cvt_pk_bf16_f32 v9, v46, v47
	s_waitcnt vmcnt(5)
	v_cvt_pk_bf16_f32 v2, v56, v57
	v_cvt_pk_bf16_f32 v3, v58, v59
	v_cvt_pk_bf16_f32 v4, v52, v53
	v_cvt_pk_bf16_f32 v5, v54, v55
	v_lshlrev_b64 v[30:31], 11, v[34:35]
	v_or_b32_e32 v34, s6, v22
	v_mov_b32_e32 v35, v1
	v_lshl_add_u64 v[30:31], s[12:13], 0, v[30:31]
	s_nop 0
	v_lshl_add_u64 v[62:63], v[30:31], 0, v[34:35]
	s_waitcnt lgkmcnt(4)
	v_mfma_f32_16x16x32_bf16 v[40:43], v[64:67], v[14:17], 0
	v_mfma_f32_16x16x32_bf16 v[40:43], v[68:71], v[10:13], v[40:43]
	v_mfma_f32_16x16x32_bf16 v[40:43], v[72:75], v[6:9], v[40:43]
	v_mfma_f32_16x16x32_bf16 v[40:43], v[76:79], v[2:5], v[40:43]
	ds_read_b64_tr_b16 v[88:89], v129 offset:9248
	ds_read_b64_tr_b16 v[90:91], v129 offset:9824
	ds_read_b64_tr_b16 v[92:93], v129 offset:13856
	ds_read_b64_tr_b16 v[94:95], v129 offset:14432
	ds_read_b64_tr_b16 v[96:97], v129 offset:64
	ds_read_b64_tr_b16 v[98:99], v129 offset:640
	ds_read_b64_tr_b16 v[100:101], v129 offset:4672
	ds_read_b64_tr_b16 v[102:103], v129 offset:5248
	s_waitcnt lgkmcnt(4)
	v_mfma_f32_16x16x32_bf16 v[44:47], v[80:83], v[14:17], 0
	v_mfma_f32_16x16x32_bf16 v[44:47], v[84:87], v[10:13], v[44:47]
	v_mfma_f32_16x16x32_bf16 v[44:47], v[88:91], v[6:9], v[44:47]
	v_mfma_f32_16x16x32_bf16 v[44:47], v[92:95], v[2:5], v[44:47]
	ds_read_b64_tr_b16 v[104:105], v129 offset:9280
	ds_read_b64_tr_b16 v[106:107], v129 offset:9856
	ds_read_b64_tr_b16 v[108:109], v129 offset:13888
	ds_read_b64_tr_b16 v[110:111], v129 offset:14464
	ds_read_b64_tr_b16 v[112:113], v129 offset:96
	ds_read_b64_tr_b16 v[114:115], v129 offset:672
	ds_read_b64_tr_b16 v[116:117], v129 offset:4704
	ds_read_b64_tr_b16 v[118:119], v129 offset:5280
	s_waitcnt vmcnt(3)
	v_lshlrev_b32_e32 v56, 16, v60
	v_add_f32_e32 v40, v39, v40
	v_and_b32_e32 v57, 0xffff0000, v60
	v_add_f32_e32 v41, v39, v41
	v_lshlrev_b32_e32 v58, 16, v61
	v_add_f32_e32 v42, v39, v42
	v_and_b32_e32 v59, 0xffff0000, v61
	v_add_f32_e32 v43, v39, v43
	v_mul_f32_e32 v56, v40, v56
	v_mul_f32_e32 v57, v41, v57
	v_mul_f32_e32 v58, v42, v58
	v_mul_f32_e32 v59, v43, v59
	v_cvt_pk_bf16_f32 v56, v56, v57
	v_cvt_pk_bf16_f32 v57, v58, v59
	global_store_dwordx2 v[62:63], v[56:57], off
	s_waitcnt lgkmcnt(4)
	v_mfma_f32_16x16x32_bf16 v[48:51], v[96:99], v[14:17], 0
	v_mfma_f32_16x16x32_bf16 v[48:51], v[100:103], v[10:13], v[48:51]
	v_mfma_f32_16x16x32_bf16 v[48:51], v[104:107], v[6:9], v[48:51]
	v_mfma_f32_16x16x32_bf16 v[48:51], v[108:111], v[2:5], v[48:51]
	ds_read_b64_tr_b16 v[120:121], v129 offset:9312
	ds_read_b64_tr_b16 v[122:123], v129 offset:9888
	ds_read_b64_tr_b16 v[124:125], v129 offset:13920
	ds_read_b64_tr_b16 v[126:127], v129 offset:14496
	s_waitcnt vmcnt(3)
	v_lshlrev_b32_e32 v56, 16, v28
	v_add_f32_e32 v44, v39, v44
	v_and_b32_e32 v57, 0xffff0000, v28
	v_add_f32_e32 v45, v39, v45
	v_lshlrev_b32_e32 v58, 16, v29
	v_add_f32_e32 v46, v39, v46
	v_and_b32_e32 v59, 0xffff0000, v29
	v_add_f32_e32 v47, v39, v47
	v_mul_f32_e32 v56, v44, v56
	v_mul_f32_e32 v57, v45, v57
	v_mul_f32_e32 v58, v46, v58
	v_mul_f32_e32 v59, v47, v59
	v_cvt_pk_bf16_f32 v56, v56, v57
	v_cvt_pk_bf16_f32 v57, v58, v59
	global_store_dwordx2 v[62:63], v[56:57], off offset:32
	s_waitcnt lgkmcnt(0)
	v_mfma_f32_16x16x32_bf16 v[52:55], v[112:115], v[14:17], 0
	v_mfma_f32_16x16x32_bf16 v[52:55], v[116:119], v[10:13], v[52:55]
	v_mfma_f32_16x16x32_bf16 v[52:55], v[120:123], v[6:9], v[52:55]
	v_mfma_f32_16x16x32_bf16 v[52:55], v[124:127], v[2:5], v[52:55]
	s_waitcnt vmcnt(3)
	v_lshlrev_b32_e32 v56, 16, v26
	v_add_f32_e32 v48, v39, v48
	v_and_b32_e32 v57, 0xffff0000, v26
	v_add_f32_e32 v49, v39, v49
	v_lshlrev_b32_e32 v58, 16, v27
	v_add_f32_e32 v50, v39, v50
	v_and_b32_e32 v59, 0xffff0000, v27
	v_add_f32_e32 v51, v39, v51
	v_mul_f32_e32 v56, v48, v56
	v_mul_f32_e32 v57, v49, v57
	v_mul_f32_e32 v58, v50, v58
	v_mul_f32_e32 v59, v51, v59
	v_cvt_pk_bf16_f32 v56, v56, v57
	v_cvt_pk_bf16_f32 v57, v58, v59
	global_store_dwordx2 v[62:63], v[56:57], off offset:64
	s_nop 7
	s_waitcnt vmcnt(3)
	v_lshlrev_b32_e32 v56, 16, v24
	v_add_f32_e32 v52, v39, v52
	v_and_b32_e32 v57, 0xffff0000, v24
	v_add_f32_e32 v53, v39, v53
	v_lshlrev_b32_e32 v58, 16, v25
	v_add_f32_e32 v54, v39, v54
	v_and_b32_e32 v59, 0xffff0000, v25
	v_add_f32_e32 v55, v39, v55
	v_mul_f32_e32 v56, v52, v56
	v_mul_f32_e32 v57, v53, v57
	v_mul_f32_e32 v58, v54, v58
	v_mul_f32_e32 v59, v55, v59
	v_cvt_pk_bf16_f32 v56, v56, v57
	v_cvt_pk_bf16_f32 v57, v58, v59
	global_store_dwordx2 v[62:63], v[56:57], off offset:96
	s_barrier
	s_cbranch_scc0 .LBB0_968
